# Sample-unit state blocks and retention phase-a operand rows of the next unit touched one unit ahead (throwaway loads)
# baseline (speedup 1.0000x reference)
.LBB0_117:
	s_mov_b64 s[100:101], 0x1e00000
	s_bfe_u32 s16, s13, 0x20005
	s_mov_b64 s[6:7], s[58:59]
	v_cvt_f32_ubyte0_e32 v0, s16
	s_lshl_b32 s30, s16, 8
	s_load_dwordx2 s[16:17], s[6:7], 0x158
	v_sub_f32_e32 v0, 0xc0a00000, v0
	v_exp_f32_e32 v0, v0
	s_mov_b64 s[10:11], s[58:59]
	s_and_b32 s15, s0, 0xfffff800
	s_and_b32 s14, s9, 0x7c0
	s_load_dwordx2 s[6:7], s[10:11], 0x158
	v_mbcnt_lo_u32_b32 v2, -1, 0
	v_mbcnt_hi_u32_b32 v2, -1, v2
	s_or_b32 s15, s15, s14
	v_add_u32_e32 v1, s61, v2
	v_lshrrev_b32_e32 v3, 4, v2
	v_and_b32_e32 v4, 15, v2
	v_bfe_u32 v24, v2, 4, 2
	v_bfe_u32 v5, v2, 3, 1
	v_ashrrev_i32_e32 v6, 3, v1
	v_lshlrev_b32_e32 v7, 3, v1
	v_readfirstlane_b32 s10, v1
	v_mul_u32_u24_e32 v9, 0x90, v4
	v_bitop3_b32 v1, v5, v3, 3 bitop3:0x78
	v_or_b32_e32 v10, 16, v4
	v_mad_u32_u24 v13, v4, s85, v198
	v_or_b32_e32 v11, 32, v4
	v_mad_u32_u24 v14, v4, s85, v199
	v_or_b32_e32 v12, 48, v4
	v_mad_u32_u24 v16, v4, s85, v200
	v_mad_u32_u24 v25, v4, s85, v201
	v_mad_u32_u24 v26, v4, s85, v202
	v_mad_u32_u24 v27, v4, s85, v203
	v_bitop3_b32 v4, v24, v5, 4 bitop3:0x36
	v_add_u32_e32 v18, s15, v6
	s_ashr_i32 s10, s10, 2
	v_lshlrev_b32_e32 v20, 4, v1
	v_lshrrev_b32_e32 v10, 3, v10
	v_lshrrev_b32_e32 v21, 3, v12
	v_lshlrev_b32_e32 v4, 4, v4
	v_sub_f32_e32 v23, 1.0, v0
	s_waitcnt lgkmcnt(0)
	v_mov_b64_e32 v[0:1], s[16:17]
	v_and_b32_e32 v5, 56, v7
	v_sub_u32_e32 v15, 63, v6
	v_add_u32_e32 v19, s14, v6
	v_lshrrev_b32_e32 v11, 3, v11
	v_bfi_b32 v22, -16, s10, v2
	v_bitop3_b32 v2, v10, v3, 3 bitop3:0x78
	v_add3_u32 v12, 0, v4, v9
	v_bitop3_b32 v4, v10, v24, 4 bitop3:0x1e
	v_bitop3_b32 v10, v21, v24, 4 bitop3:0x1e
	v_mad_i64_i32 v[0:1], s[10:11], v18, s83, v[0:1]
	v_lshlrev_b32_e32 v156, 1, v5
	v_lshl_add_u32 v28, v5, 2, 0
	v_cvt_f32_i32_e32 v30, v15
	v_cvt_f32_i32_e32 v40, v19
	v_add3_u32 v15, 0, v20, v9
	v_bitop3_b32 v19, v11, v3, 3 bitop3:0x78
	v_bitop3_b32 v9, v11, v24, 4 bitop3:0x1e
	v_log_f32_e32 v31, v23
	v_lshl_add_u32 v34, v10, 4, 0
	v_ashrrev_i32_e32 v23, 31, v22
	v_lshl_add_u64 v[10:11], v[0:1], 0, s[30:31]
	v_or_b32_e32 v17, 4, v24
	v_bitop3_b32 v7, v6, 56, v7 bitop3:0x48
	v_and_b32_e32 v6, 7, v6
	v_mul_u32_u24_e32 v5, 0x48, v5
	v_bitop3_b32 v3, v21, v3, 3 bitop3:0x78
	v_add_u32_e32 v18, 0x22400, v28
	v_mul_lo_u32 v21, v22, s85
	v_lshrrev_b32_e32 v28, 3, v22
	v_lshlrev_b64 v[22:23], 8, v[22:23]
	v_lshl_add_u64 v[10:11], v[10:11], 0, v[156:157]
	v_or3_b32 v20, v7, v6, v5
	v_lshl_add_u32 v29, v2, 4, 0
	v_lshl_add_u32 v19, v19, 4, 0
	v_lshl_add_u32 v32, v3, 4, 0
	v_lshl_add_u32 v33, v4, 4, 0
	v_lshl_add_u32 v9, v9, 4, 0
	v_add_u32_e32 v35, 0, v21
	v_bitop3_b32 v36, v28, v24, 7 bitop3:0x6c
	v_bitop3_b32 v28, v28, v17, 7 bitop3:0x6c
	v_lshl_or_b32 v22, v24, 6, v22
	v_lshl_add_u64 v[10:11], v[10:11], 0, s[46:47]
	ds_read_b128 v[4:7], v18
	ds_read_b128 v[0:3], v18 offset:16
	v_lshl_add_u32 v62, v20, 1, 0
	v_add_u32_e32 v63, v29, v13
	v_add_u32_e32 v64, v19, v14
	v_add_u32_e32 v21, v29, v25
	v_add_u32_e32 v20, v19, v26
	v_add_u32_e32 v19, v32, v27
	v_add_u32_e32 v18, v33, v13
	v_add_u32_e32 v17, v9, v14
	v_add_u32_e32 v14, v33, v25
	v_add_u32_e32 v13, v9, v26
	v_add_u32_e32 v9, v34, v27
	v_lshl_add_u32 v67, v28, 4, v35
	v_lshl_add_u64 v[38:39], s[6:7], 0, v[22:23]
	global_load_dwordx4 v[22:25], v[10:11], off offset:1024
	global_load_dwordx4 v[26:29], v[10:11], off offset:1152
	v_add_u32_e32 v65, v32, v16
	v_add_u32_e32 v16, v34, v16
	v_lshl_add_u32 v66, v36, 4, v35
	v_mul_f32_e32 v41, v31, v30
	global_load_dwordx4 v[30:33], v[10:11], off offset:2048
	global_load_dwordx4 v[34:37], v[10:11], off offset:2176
	v_lshl_add_u64 v[140:141], v[10:11], 0, s[100:101]
	v_lshl_add_u64 v[10:11], v[38:39], 0, s[2:3]
	v_exp_f32_e32 v68, v41
	s_waitcnt lgkmcnt(0)
	v_mul_f32_e32 v4, v4, v40
	v_mul_f32_e32 v5, v5, v40
	v_mul_f32_e32 v6, v6, v40
	v_mul_f32_e32 v7, v7, v40
	v_mul_f32_e32 v38, v0, v40
	v_mul_f32_e32 v41, v1, v40
	v_mul_f32_e32 v42, v2, v40
	v_mul_f32_e32 v44, v3, v40
	v_cvt_f64_f32_e32 v[0:1], v4
	v_cvt_f64_f32_e32 v[2:3], v5
	v_cvt_f64_f32_e32 v[4:5], v6
	v_cvt_f64_f32_e32 v[6:7], v7
	v_cvt_f64_f32_e32 v[38:39], v38
	v_cvt_f64_f32_e32 v[40:41], v41
	v_cvt_f64_f32_e32 v[42:43], v42
	v_cvt_f64_f32_e32 v[44:45], v44
	v_mul_f64 v[46:47], v[0:1], s[86:87]
	v_mul_f64 v[48:49], v[2:3], s[86:87]
	v_mul_f64 v[50:51], v[4:5], s[86:87]
	v_mul_f64 v[52:53], v[6:7], s[86:87]
	v_mul_f64 v[54:55], v[38:39], s[86:87]
	v_mul_f64 v[56:57], v[40:41], s[86:87]
	v_mul_f64 v[58:59], v[42:43], s[86:87]
	v_mul_f64 v[60:61], v[44:45], s[86:87]
	v_rndne_f64_e32 v[46:47], v[46:47]
	v_rndne_f64_e32 v[48:49], v[48:49]
	v_rndne_f64_e32 v[50:51], v[50:51]
	v_rndne_f64_e32 v[52:53], v[52:53]
	v_rndne_f64_e32 v[54:55], v[54:55]
	v_rndne_f64_e32 v[56:57], v[56:57]
	v_rndne_f64_e32 v[58:59], v[58:59]
	v_rndne_f64_e32 v[60:61], v[60:61]
	v_fma_f64 v[0:1], v[0:1], s[86:87], -v[46:47]
	v_fma_f64 v[2:3], v[2:3], s[86:87], -v[48:49]
	v_fma_f64 v[4:5], v[4:5], s[86:87], -v[50:51]
	v_fma_f64 v[6:7], v[6:7], s[86:87], -v[52:53]
	v_fma_f64 v[38:39], v[38:39], s[86:87], -v[54:55]
	v_fma_f64 v[40:41], v[40:41], s[86:87], -v[56:57]
	v_fma_f64 v[42:43], v[42:43], s[86:87], -v[58:59]
	v_fma_f64 v[44:45], v[44:45], s[86:87], -v[60:61]
	v_cvt_f32_f64_e32 v0, v[0:1]
	v_cvt_f32_f64_e32 v1, v[2:3]
	v_cvt_f32_f64_e32 v2, v[4:5]
	v_cvt_f32_f64_e32 v3, v[6:7]
	v_cvt_f32_f64_e32 v4, v[38:39]
	v_cvt_f32_f64_e32 v5, v[40:41]
	v_cvt_f32_f64_e32 v6, v[42:43]
	v_cvt_f32_f64_e32 v7, v[44:45]
	v_sin_f32_e32 v38, v0
	v_cos_f32_e32 v0, v0
	v_sin_f32_e32 v39, v1
	v_cos_f32_e32 v1, v1
	v_sin_f32_e32 v40, v2
	v_cos_f32_e32 v2, v2
	v_sin_f32_e32 v41, v3
	v_cos_f32_e32 v3, v3
	v_sin_f32_e32 v42, v4
	v_cos_f32_e32 v4, v4
	v_sin_f32_e32 v43, v5
	v_cos_f32_e32 v5, v5
	v_sin_f32_e32 v44, v6
	v_cos_f32_e32 v6, v6
	v_sin_f32_e32 v45, v7
	v_cos_f32_e32 v7, v7
	s_waitcnt vmcnt(0)
	s_add_i32 s100, s13, s18
	s_cmpk_gt_i32 s100, 0x3ff
	s_cbranch_scc1 .Lra64pf_skip
	global_load_dwordx4 v[144:147], v[140:141], off offset:1024
	global_load_dwordx4 v[144:147], v[140:141], off offset:1152
	global_load_dwordx4 v[144:147], v[140:141], off offset:2048
	global_load_dwordx4 v[144:147], v[140:141], off offset:2176
.Lra64pf_skip:
	ds_write_b16 v62, v30 offset:44032
	ds_write_b16 v62, v34 offset:53248
	ds_write_b16_d16_hi v62, v30 offset:44176
	ds_write_b16_d16_hi v62, v34 offset:53392
	ds_write_b16 v62, v31 offset:44320
	ds_write_b16 v62, v35 offset:53536
	ds_write_b16_d16_hi v62, v31 offset:44464
	ds_write_b16_d16_hi v62, v35 offset:53680
	ds_write_b16 v62, v32 offset:44608
	ds_write_b16 v62, v36 offset:53824
	ds_write_b16_d16_hi v62, v32 offset:44752
	ds_write_b16_d16_hi v62, v36 offset:53968
	ds_write_b16 v62, v33 offset:44896
	ds_write_b16 v62, v37 offset:54112
	ds_write_b16_d16_hi v62, v33 offset:45040
	ds_write_b16_d16_hi v62, v37 offset:54256
	v_lshlrev_b32_e32 v50, 16, v26
	v_and_b32_e32 v26, 0xffff0000, v26
	v_lshlrev_b32_e32 v51, 16, v27
	v_and_b32_e32 v27, 0xffff0000, v27
	v_lshlrev_b32_e32 v52, 16, v28
	v_and_b32_e32 v28, 0xffff0000, v28
	v_lshlrev_b32_e32 v53, 16, v29
	v_and_b32_e32 v29, 0xffff0000, v29
	v_lshlrev_b32_e32 v46, 16, v22
	v_and_b32_e32 v22, 0xffff0000, v22
	v_lshlrev_b32_e32 v47, 16, v23
	v_and_b32_e32 v23, 0xffff0000, v23
	v_lshlrev_b32_e32 v48, 16, v24
	v_and_b32_e32 v24, 0xffff0000, v24
	v_lshlrev_b32_e32 v49, 16, v25
	v_and_b32_e32 v25, 0xffff0000, v25
	v_mul_f32_e32 v30, v38, v50
	v_mul_f32_e32 v31, v0, v50
	v_mul_f32_e32 v32, v39, v26
	v_mul_f32_e32 v26, v1, v26
	v_mul_f32_e32 v33, v40, v51
	v_mul_f32_e32 v34, v2, v51
	v_mul_f32_e32 v35, v41, v27
	v_mul_f32_e32 v27, v3, v27
	v_mul_f32_e32 v36, v42, v52
	v_mul_f32_e32 v37, v4, v52
	v_mul_f32_e32 v50, v43, v28
	v_mul_f32_e32 v28, v5, v28
	v_mul_f32_e32 v51, v44, v53
	v_mul_f32_e32 v52, v6, v53
	v_mul_f32_e32 v53, v45, v29
	v_mul_f32_e32 v29, v7, v29
	v_mul_f32_e32 v68, 0x3db504f3, v68
	v_fma_f32 v0, v0, v46, -v30
	v_fmac_f32_e32 v31, v38, v46
	v_fma_f32 v1, v1, v22, -v32
	v_fmac_f32_e32 v26, v39, v22
	v_fma_f32 v2, v2, v47, -v33
	v_fmac_f32_e32 v34, v40, v47
	v_fma_f32 v3, v3, v23, -v35
	v_fmac_f32_e32 v27, v41, v23
	v_fma_f32 v4, v4, v48, -v36
	v_fmac_f32_e32 v37, v42, v48
	v_fma_f32 v5, v5, v24, -v50
	v_fmac_f32_e32 v28, v43, v24
	v_fma_f32 v6, v6, v49, -v51
	v_fmac_f32_e32 v52, v44, v49
	v_fma_f32 v7, v7, v25, -v53
	v_fmac_f32_e32 v29, v45, v25
	v_mul_f32_e32 v0, v68, v0
	v_mul_f32_e32 v22, v68, v31
	v_mul_f32_e32 v1, v68, v1
	v_mul_f32_e32 v23, v68, v26
	v_mul_f32_e32 v2, v68, v2
	v_mul_f32_e32 v24, v68, v34
	v_mul_f32_e32 v3, v68, v3
	v_mul_f32_e32 v25, v68, v27
	v_mul_f32_e32 v4, v68, v4
	v_mul_f32_e32 v26, v68, v37
	v_mul_f32_e32 v5, v68, v5
	v_mul_f32_e32 v27, v68, v28
	v_mul_f32_e32 v6, v68, v6
	v_mul_f32_e32 v28, v68, v52
	v_mul_f32_e32 v7, v68, v7
	v_mul_f32_e32 v29, v68, v29
	v_bfe_u32 v30, v0, 16, 1
	v_bfe_u32 v31, v22, 16, 1
	v_bfe_u32 v32, v1, 16, 1
	v_bfe_u32 v33, v23, 16, 1
	v_bfe_u32 v34, v2, 16, 1
	v_bfe_u32 v35, v24, 16, 1
	v_bfe_u32 v36, v3, 16, 1
	v_bfe_u32 v37, v25, 16, 1
	v_bfe_u32 v38, v4, 16, 1
	v_bfe_u32 v39, v26, 16, 1
	v_bfe_u32 v40, v5, 16, 1
	v_bfe_u32 v41, v27, 16, 1
	v_bfe_u32 v42, v6, 16, 1
	v_bfe_u32 v43, v28, 16, 1
	v_bfe_u32 v44, v7, 16, 1
	v_bfe_u32 v45, v29, 16, 1
	v_add3_u32 v0, v0, v30, s54
	v_add3_u32 v22, v22, v31, s54
	v_add3_u32 v1, v1, v32, s54
	v_add3_u32 v23, v23, v33, s54
	v_add3_u32 v2, v2, v34, s54
	v_add3_u32 v24, v24, v35, s54
	v_add3_u32 v3, v3, v36, s54
	v_add3_u32 v25, v25, v37, s54
	v_add3_u32 v4, v4, v38, s54
	v_add3_u32 v26, v26, v39, s54
	v_add3_u32 v5, v5, v40, s54
	v_add3_u32 v27, v27, v41, s54
	v_add3_u32 v6, v6, v42, s54
	v_add3_u32 v28, v28, v43, s54
	v_add3_u32 v7, v7, v44, s54
	v_add3_u32 v29, v29, v45, s54
	ds_write_b16_d16_hi v62, v0
	ds_write_b16_d16_hi v62, v22 offset:9216
	ds_write_b16_d16_hi v62, v1 offset:144
	ds_write_b16_d16_hi v62, v23 offset:9360
	ds_write_b16_d16_hi v62, v2 offset:288
	ds_write_b16_d16_hi v62, v24 offset:9504
	ds_write_b16_d16_hi v62, v3 offset:432
	ds_write_b16_d16_hi v62, v25 offset:9648
	ds_write_b16_d16_hi v62, v4 offset:576
	ds_write_b16_d16_hi v62, v26 offset:9792
	ds_write_b16_d16_hi v62, v5 offset:720
	ds_write_b16_d16_hi v62, v27 offset:9936
	ds_write_b16_d16_hi v62, v6 offset:864
	ds_write_b16_d16_hi v62, v28 offset:10080
	ds_write_b16_d16_hi v62, v7 offset:1008
	ds_write_b16_d16_hi v62, v29 offset:10224
	s_waitcnt lgkmcnt(0)
	s_barrier
	ds_read_b128 v[0:3], v15 offset:44032
	ds_read_b128 v[4:7], v66
	ds_read_b128 v[22:25], v63 offset:44032
	ds_read_b128 v[26:29], v64 offset:44032
	ds_read_b128 v[38:41], v21 offset:44032
	ds_read_b128 v[30:33], v65 offset:44032
	ds_read_b128 v[34:37], v15 offset:53248
	ds_read_b128 v[42:45], v20 offset:44032
	ds_read_b128 v[46:49], v19 offset:44032
	ds_read_b128 v[18:21], v18 offset:44032
	s_waitcnt lgkmcnt(8)
	v_mfma_f32_16x16x32_bf16 v[0:3], v[0:3], v[4:7], 0
	ds_read_b128 v[50:53], v12 offset:44032
	v_mov_b32_e32 v8, 1.0
	s_add_i32 s13, s13, s18
	s_waitcnt lgkmcnt(8)
	v_mfma_f32_16x16x32_bf16 v[22:25], v[22:25], v[4:7], 0
	s_add_i32 s0, s0, s1
	s_add_i32 s9, s9, s12
	s_add_u32 s2, s2, s4
	s_waitcnt lgkmcnt(7)
	v_mfma_f32_16x16x32_bf16 v[26:29], v[26:29], v[4:7], 0
	s_addc_u32 s3, s3, s5
	s_cmpk_gt_i32 s13, 0x3ff
	s_waitcnt lgkmcnt(5)
	v_mfma_f32_16x16x32_bf16 v[30:33], v[30:33], v[4:7], 0
	s_waitcnt lgkmcnt(4)
	v_mfma_f32_16x16x32_bf16 v[34:37], v[34:37], v[4:7], 0
	v_mfma_f32_16x16x32_bf16 v[38:41], v[38:41], v[4:7], 0
	s_waitcnt lgkmcnt(3)
	v_mfma_f32_16x16x32_bf16 v[42:45], v[42:45], v[4:7], 0
	s_waitcnt lgkmcnt(2)
	v_mfma_f32_16x16x32_bf16 v[4:7], v[46:49], v[4:7], 0
	ds_read_b128 v[46:49], v67
	s_waitcnt lgkmcnt(0)
	v_mfma_f32_16x16x32_bf16 v[18:21], v[18:21], v[46:49], v[22:25]
	s_nop 2
	ds_read_b128 v[22:25], v17 offset:44032
	s_waitcnt lgkmcnt(0)
	v_mfma_f32_16x16x32_bf16 v[22:25], v[22:25], v[46:49], v[26:29]
	s_nop 2
	ds_read_b128 v[26:29], v16 offset:44032
	ds_read_b128 v[14:17], v14 offset:44032
	s_waitcnt lgkmcnt(1)
	v_mfma_f32_16x16x32_bf16 v[26:29], v[26:29], v[46:49], v[30:33]
	s_nop 2
	ds_read_b128 v[30:33], v12 offset:53248
	s_waitcnt lgkmcnt(0)
	v_mfma_f32_16x16x32_bf16 v[30:33], v[30:33], v[46:49], v[34:37]
	s_nop 2
	ds_read_b128 v[34:37], v13 offset:44032
	v_mfma_f32_16x16x32_bf16 v[14:17], v[14:17], v[46:49], v[38:41]
	s_nop 2
	ds_read_b128 v[38:41], v9 offset:44032
	v_mfma_f32_16x16x32_bf16 v[0:3], v[50:53], v[46:49], v[0:3]
	s_nop 0
	v_mul_f32_e64 v12, v20, v8
	v_mul_f32_e64 v13, v21, v8
	s_waitcnt lgkmcnt(1)
	v_mfma_f32_16x16x32_bf16 v[34:37], v[34:37], v[46:49], v[42:45]
	v_mul_f32_e64 v18, v18, v8
	v_mul_f32_e64 v19, v19, v8
	s_nop 0
	v_pk_mul_f32 v[2:3], v[2:3], v[8:9] op_sel_hi:[1,0]
	v_pk_mul_f32 v[0:1], v[0:1], v[8:9] op_sel_hi:[1,0]
	s_waitcnt lgkmcnt(0)
	v_mfma_f32_16x16x32_bf16 v[4:7], v[38:41], v[46:49], v[4:7]
	v_cvt_pk_bf16_f32 v0, v0, v1
	v_cvt_pk_bf16_f32 v1, v2, v3
	v_cvt_pk_bf16_f32 v2, v18, v19
	v_cvt_pk_bf16_f32 v3, v12, v13
	v_mul_f32_e64 v20, v24, v8
	v_mul_f32_e64 v21, v25, v8
	v_pk_mul_f32 v[22:23], v[22:23], v[8:9] op_sel_hi:[1,0]
	v_pk_mul_f32 v[24:25], v[28:29], v[8:9] op_sel_hi:[1,0]
	v_pk_mul_f32 v[26:27], v[26:27], v[8:9] op_sel_hi:[1,0]
	global_store_dwordx4 v[10:11], v[0:3], off
	v_pk_mul_f32 v[28:29], v[32:33], v[8:9] op_sel_hi:[1,0]
	v_pk_mul_f32 v[30:31], v[30:31], v[8:9] op_sel_hi:[1,0]
	v_cvt_pk_bf16_f32 v0, v22, v23
	v_cvt_pk_bf16_f32 v1, v20, v21
	v_cvt_pk_bf16_f32 v2, v26, v27
	v_cvt_pk_bf16_f32 v3, v24, v25
	v_pk_mul_f32 v[16:17], v[16:17], v[8:9] op_sel_hi:[1,0]
	v_pk_mul_f32 v[14:15], v[14:15], v[8:9] op_sel_hi:[1,0]
	global_store_dwordx4 v[10:11], v[0:3], off offset:16
	v_pk_mul_f32 v[32:33], v[36:37], v[8:9] op_sel_hi:[1,0]
	v_pk_mul_f32 v[34:35], v[34:35], v[8:9] op_sel_hi:[1,0]
	v_cvt_pk_bf16_f32 v0, v30, v31
	v_cvt_pk_bf16_f32 v1, v28, v29
	v_cvt_pk_bf16_f32 v2, v14, v15
	v_cvt_pk_bf16_f32 v3, v16, v17
	v_pk_mul_f32 v[6:7], v[6:7], v[8:9] op_sel_hi:[1,0]
	v_pk_mul_f32 v[4:5], v[4:5], v[8:9] op_sel_hi:[1,0]
	global_store_dwordx4 v[10:11], v[0:3], off offset:32
	s_nop 1
	v_cvt_pk_bf16_f32 v0, v34, v35
	v_cvt_pk_bf16_f32 v1, v32, v33
	v_cvt_pk_bf16_f32 v2, v4, v5
	v_cvt_pk_bf16_f32 v3, v6, v7
	global_store_dwordx4 v[10:11], v[0:3], off offset:48
	s_barrier
	s_cbranch_scc0 .LBB0_117

.LBB0_119:
	s_mov_b64 s[0:1], s[58:59]
	s_load_dwordx2 s[16:17], s[0:1], 0x158
	s_mov_b64 s[0:1], s[58:59]
	s_load_dwordx2 s[18:19], s[0:1], 0x20
	s_mov_b64 s[0:1], s[58:59]
	s_load_dwordx2 s[4:5], s[0:1], 0x150
	s_mov_b64 s[0:1], s[58:59]
	s_load_dwordx2 s[6:7], s[0:1], 0xa8
	s_mov_b64 s[0:1], s[58:59]
	s_load_dwordx2 s[10:11], s[0:1], 0x158
	v_mbcnt_lo_u32_b32 v1, -1, 0
	v_mbcnt_hi_u32_b32 v1, -1, v1
	s_lshl_b32 s1, s2, 1
	v_add_u32_e32 v116, s61, v1
	s_and_b32 s1, s1, -8
	s_ashr_i32 s3, s2, 31
	v_ashrrev_i32_e32 v98, 2, v116
	s_and_b32 s0, s2, 3
	s_add_i32 s14, s1, 0x4000
	s_lshl_b64 s[12:13], s[2:3], 14
	s_lshl_b64 s[20:21], s[2:3], 16
	v_and_b32_e32 v102, 0xffffffe0, v98
	s_waitcnt lgkmcnt(0)
	s_add_u32 s18, s18, s20
	v_and_b32_e32 v0, 0x7f, v116
	v_or_b32_e32 v4, 1, v102
	v_or_b32_e32 v6, 2, v102
	v_or_b32_e32 v8, 3, v102
	v_or_b32_e32 v12, 5, v102
	v_or_b32_e32 v14, 6, v102
	s_addc_u32 s19, s19, s21
	v_lshlrev_b32_e32 v156, 2, v0
	v_ashrrev_i32_e32 v103, 31, v102
	v_ashrrev_i32_e32 v5, 31, v4
	v_ashrrev_i32_e32 v7, 31, v6
	v_ashrrev_i32_e32 v9, 31, v8
	v_or_b32_e32 v10, 4, v102
	v_ashrrev_i32_e32 v13, 31, v12
	v_ashrrev_i32_e32 v15, 31, v14
	v_or_b32_e32 v16, 7, v102
	v_lshl_add_u64 v[94:95], s[18:19], 0, v[156:157]
	s_cmpk_lt_i32 s2, 0x100
	s_cbranch_scc0 .Lrsmp_skip
	v_lshlrev_b32_e32 v140, 7, v116
	v_add_u32_e32 v140, 0x1000000, v140
	v_mov_b32_e32 v141, 0
	v_lshl_add_u64 v[140:141], s[18:19], 0, v[140:141]
	global_load_dword v142, v[140:141], off
.Lrsmp_skip:
	v_lshlrev_b64 v[2:3], 9, v[102:103]
	v_lshlrev_b64 v[4:5], 9, v[4:5]
	v_lshlrev_b64 v[6:7], 9, v[6:7]
	v_lshlrev_b64 v[8:9], 9, v[8:9]
	v_ashrrev_i32_e32 v11, 31, v10
	v_lshlrev_b64 v[12:13], 9, v[12:13]
	v_lshlrev_b64 v[14:15], 9, v[14:15]
	v_ashrrev_i32_e32 v17, 31, v16
	v_lshl_add_u64 v[18:19], v[94:95], 0, v[2:3]
	v_lshl_add_u64 v[20:21], v[94:95], 0, v[4:5]
	v_lshl_add_u64 v[22:23], v[94:95], 0, v[6:7]
	v_lshl_add_u64 v[24:25], v[94:95], 0, v[8:9]
	v_lshlrev_b64 v[10:11], 9, v[10:11]
	v_lshl_add_u64 v[30:31], v[94:95], 0, v[12:13]
	v_lshl_add_u64 v[32:33], v[94:95], 0, v[14:15]
	v_lshlrev_b64 v[16:17], 9, v[16:17]
	v_lshl_add_u64 v[28:29], v[94:95], 0, v[10:11]
	v_lshl_add_u64 v[34:35], v[94:95], 0, v[16:17]
	global_load_dword v26, v[18:19], off nt
	global_load_dword v27, v[20:21], off nt
	s_nop 0
	global_load_dword v22, v[22:23], off nt
	s_nop 0
	global_load_dword v23, v[24:25], off nt
	global_load_dword v20, v[28:29], off nt
	global_load_dword v21, v[30:31], off nt
	global_load_dword v18, v[32:33], off nt
	global_load_dword v19, v[34:35], off nt
	v_or_b32_e32 v24, 8, v102
	v_or_b32_e32 v30, 10, v102
	v_or_b32_e32 v32, 11, v102
	v_or_b32_e32 v42, 14, v102
	v_or_b32_e32 v44, 15, v102
	v_ashrrev_i32_e32 v25, 31, v24
	v_or_b32_e32 v28, 9, v102
	v_ashrrev_i32_e32 v31, 31, v30
	v_ashrrev_i32_e32 v33, 31, v32
	v_or_b32_e32 v38, 12, v102
	v_or_b32_e32 v40, 13, v102
	v_ashrrev_i32_e32 v43, 31, v42
	v_ashrrev_i32_e32 v45, 31, v44
	v_lshlrev_b64 v[24:25], 9, v[24:25]
	v_ashrrev_i32_e32 v29, 31, v28
	v_lshlrev_b64 v[30:31], 9, v[30:31]
	v_lshlrev_b64 v[32:33], 9, v[32:33]
	v_ashrrev_i32_e32 v39, 31, v38
	v_ashrrev_i32_e32 v41, 31, v40
	v_lshlrev_b64 v[42:43], 9, v[42:43]
	v_lshlrev_b64 v[44:45], 9, v[44:45]
	v_lshl_add_u64 v[34:35], v[94:95], 0, v[24:25]
	v_lshlrev_b64 v[28:29], 9, v[28:29]
	v_lshl_add_u64 v[46:47], v[94:95], 0, v[30:31]
	v_lshl_add_u64 v[48:49], v[94:95], 0, v[32:33]
	v_lshlrev_b64 v[38:39], 9, v[38:39]
	v_lshlrev_b64 v[40:41], 9, v[40:41]
	v_lshl_add_u64 v[58:59], v[94:95], 0, v[42:43]
	v_lshl_add_u64 v[60:61], v[94:95], 0, v[44:45]
	v_lshl_add_u64 v[36:37], v[94:95], 0, v[28:29]
	v_lshl_add_u64 v[52:53], v[94:95], 0, v[38:39]
	v_lshl_add_u64 v[56:57], v[94:95], 0, v[40:41]
	global_load_dword v54, v[34:35], off nt
	global_load_dword v55, v[36:37], off nt
	global_load_dword v50, v[46:47], off nt
	global_load_dword v51, v[48:49], off nt
	s_nop 0
	global_load_dword v48, v[52:53], off nt
	global_load_dword v49, v[56:57], off nt
	global_load_dword v46, v[58:59], off nt
	global_load_dword v47, v[60:61], off nt
	v_or_b32_e32 v34, 16, v102
	v_or_b32_e32 v58, 18, v102
	v_or_b32_e32 v60, 19, v102
	v_ashrrev_i32_e32 v35, 31, v34
	v_or_b32_e32 v36, 17, v102
	v_ashrrev_i32_e32 v59, 31, v58
	v_ashrrev_i32_e32 v61, 31, v60
	v_or_b32_e32 v62, 20, v102
	v_or_b32_e32 v64, 21, v102
	v_or_b32_e32 v66, 22, v102
	v_or_b32_e32 v68, 23, v102
	v_lshlrev_b64 v[52:53], 9, v[34:35]
	v_ashrrev_i32_e32 v37, 31, v36
	v_lshlrev_b64 v[58:59], 9, v[58:59]
	v_lshlrev_b64 v[60:61], 9, v[60:61]
	v_ashrrev_i32_e32 v63, 31, v62
	v_ashrrev_i32_e32 v65, 31, v64
	v_ashrrev_i32_e32 v67, 31, v66
	v_ashrrev_i32_e32 v69, 31, v68
	v_lshl_add_u64 v[34:35], v[94:95], 0, v[52:53]
	v_lshlrev_b64 v[56:57], 9, v[36:37]
	v_lshl_add_u64 v[70:71], v[94:95], 0, v[58:59]
	v_lshl_add_u64 v[72:73], v[94:95], 0, v[60:61]
	v_lshlrev_b64 v[62:63], 9, v[62:63]
	v_lshlrev_b64 v[64:65], 9, v[64:65]
	v_lshlrev_b64 v[66:67], 9, v[66:67]
	v_lshlrev_b64 v[68:69], 9, v[68:69]
	v_lshl_add_u64 v[36:37], v[94:95], 0, v[56:57]
	v_lshl_add_u64 v[76:77], v[94:95], 0, v[62:63]
	v_lshl_add_u64 v[80:81], v[94:95], 0, v[64:65]
	v_lshl_add_u64 v[82:83], v[94:95], 0, v[66:67]
	v_lshl_add_u64 v[84:85], v[94:95], 0, v[68:69]
	global_load_dword v78, v[34:35], off nt
	global_load_dword v79, v[36:37], off nt
	global_load_dword v74, v[70:71], off nt
	global_load_dword v75, v[72:73], off nt
	s_nop 0
	global_load_dword v72, v[76:77], off nt
	global_load_dword v73, v[80:81], off nt
	global_load_dword v70, v[82:83], off nt
	global_load_dword v71, v[84:85], off nt
	v_or_b32_e32 v34, 24, v102
	v_ashrrev_i32_e32 v35, 31, v34
	v_lshlrev_b64 v[76:77], 9, v[34:35]
	v_or_b32_e32 v34, 25, v102
	v_ashrrev_i32_e32 v35, 31, v34
	v_lshlrev_b64 v[80:81], 9, v[34:35]
	v_or_b32_e32 v34, 26, v102
	v_ashrrev_i32_e32 v35, 31, v34
	v_ashrrev_i32_e32 v36, 6, v116
	v_lshlrev_b64 v[82:83], 9, v[34:35]
	v_and_b32_e32 v34, 63, v1
	v_add_u32_e32 v1, s14, v36
	v_mov_b64_e32 v[86:87], s[16:17]
	v_mad_i64_i32 v[86:87], s[16:17], v1, s83, v[86:87]
	s_lshl_b32 s30, s0, 8
	v_lshl_add_u64 v[86:87], v[86:87], 0, s[30:31]
	v_lshlrev_b32_e32 v88, 1, v34
	v_mov_b32_e32 v89, v157
	v_lshl_add_u64 v[86:87], v[86:87], 0, v[88:89]
	s_mov_b32 s1, 0x12f00000
	v_lshl_add_u64 v[92:93], v[86:87], 0, s[46:47]
	v_add_co_u32_e32 v86, vcc, s1, v86
	v_or_b32_e32 v84, 27, v102
	s_nop 0
	v_addc_co_u32_e32 v87, vcc, 0, v87, vcc
	global_load_ushort v1, v[86:87], off
	global_load_ushort v35, v[92:93], off offset:128
	global_load_ushort v37, v[92:93], off offset:1024
	global_load_ushort v103, v[92:93], off offset:1152
	v_or_b32_e32 v86, 28, v102
	v_or_b32_e32 v88, 29, v102
	v_or_b32_e32 v90, 30, v102
	v_or_b32_e32 v98, 31, v98
	v_ashrrev_i32_e32 v85, 31, v84
	v_ashrrev_i32_e32 v87, 31, v86
	v_ashrrev_i32_e32 v89, 31, v88
	v_ashrrev_i32_e32 v91, 31, v90
	v_ashrrev_i32_e32 v99, 31, v98
	v_lshl_add_u64 v[96:97], v[94:95], 0, v[76:77]
	v_lshl_add_u64 v[100:101], v[94:95], 0, v[80:81]
	v_lshl_add_u64 v[104:105], v[94:95], 0, v[82:83]
	v_lshlrev_b64 v[84:85], 9, v[84:85]
	v_lshlrev_b64 v[86:87], 9, v[86:87]
	v_lshlrev_b64 v[88:89], 9, v[88:89]
	v_lshlrev_b64 v[90:91], 9, v[90:91]
	global_load_ushort v117, v[92:93], off offset:2048
	global_load_ushort v118, v[92:93], off offset:2176
	global_load_ushort v119, v[92:93], off offset:3072
	global_load_ushort v120, v[92:93], off offset:3200
	v_lshlrev_b64 v[92:93], 9, v[98:99]
	v_lshl_add_u64 v[106:107], v[94:95], 0, v[84:85]
	v_lshl_add_u64 v[108:109], v[94:95], 0, v[86:87]
	v_lshl_add_u64 v[110:111], v[94:95], 0, v[88:89]
	v_lshl_add_u64 v[112:113], v[94:95], 0, v[90:91]
	v_lshl_add_u64 v[114:115], v[94:95], 0, v[92:93]
	global_load_dword v98, v[96:97], off nt
	global_load_dword v99, v[100:101], off nt
	s_nop 0
	global_load_dword v96, v[104:105], off nt
	global_load_dword v97, v[106:107], off nt
	global_load_dword v94, v[108:109], off nt
	global_load_dword v95, v[110:111], off nt
	global_load_dword v100, v[112:113], off nt
	s_nop 0
	global_load_dword v104, v[114:115], off nt
	v_lshlrev_b32_e32 v110, 2, v34
	v_add_u32_e32 v106, 0, v110
	v_add_u32_e32 v106, 0x22400, v106
	v_add_u32_e32 v105, 0x4000, v36
	ds_read_b32 v106, v106
	v_cvt_f32_i32_e32 v105, v105
	v_cvt_f32_ubyte0_e32 v101, s0
	v_sub_f32_e32 v101, 0xc0a00000, v101
	v_exp_f32_e32 v101, v101
	s_waitcnt lgkmcnt(0)
	v_mul_f32_e32 v105, v106, v105
	v_cvt_f64_f32_e32 v[106:107], v105
	v_mul_f64 v[108:109], v[106:107], s[86:87]
	v_rndne_f64_e32 v[108:109], v[108:109]
	v_fma_f64 v[106:107], v[106:107], s[86:87], -v[108:109]
	v_cvt_f32_f64_e32 v105, v[106:107]
	v_sin_f32_e32 v106, v105
	v_cos_f32_e32 v105, v105
	v_lshl_or_b32 v108, v36, 9, v110
	v_add_u32_e32 v108, 0, v108
	v_sub_f32_e32 v101, 1.0, v101
	s_lshl_b32 s0, s0, 7
	s_mov_b32 s1, 0
	s_waitcnt vmcnt(0)
	v_lshlrev_b32_e32 v1, 16, v1
	v_lshlrev_b32_e32 v35, 16, v35
	v_mul_f32_e32 v107, v106, v35
	v_mul_f32_e32 v35, v105, v35
	v_lshlrev_b32_e32 v103, 16, v103
	v_fma_f32 v107, v105, v1, -v107
	v_fmac_f32_e32 v35, v106, v1
	v_lshlrev_b32_e32 v37, 16, v37
	ds_write2st64_b32 v108, v107, v35 offset0:32 offset1:33
	v_mul_f32_e32 v1, v106, v103
	v_mul_f32_e32 v35, v105, v103
	v_fma_f32 v1, v105, v37, -v1
	v_fmac_f32_e32 v35, v106, v37
	v_mul_f32_e32 v1, 0x3db504f3, v1
	v_mul_f32_e32 v35, 0x3db504f3, v35
	ds_write2st64_b32 v108, v1, v35 offset0:16 offset1:17
	ds_write2st64_b32 v108, v101, v101 offset1:1
	v_lshlrev_b32_e32 v37, 2, v116
	v_and_b32_e32 v37, 0xfffffe00, v37
	v_add_u32_e32 v37, 0x5000, v37
	v_lshlrev_b32_e32 v1, 16, v117
	v_lshlrev_b32_e32 v35, 16, v118
	ds_write2st64_b32 v108, v1, v35 offset0:48 offset1:49
	v_lshlrev_b32_e32 v1, 16, v119
	v_lshlrev_b32_e32 v35, 16, v120
	ds_write2st64_b32 v108, v1, v35 offset0:64 offset1:65
	v_add_u32_e32 v1, 0, v156
	v_lshl_add_u32 v35, v102, 2, 0
	s_waitcnt lgkmcnt(0)
	s_barrier

.LBB0_920:
	s_mov_b64 s[0:1], s[58:59]
	s_load_dwordx2 s[18:19], s[0:1], 0x158
	s_mov_b64 s[0:1], s[58:59]
	s_mov_b64 s[4:5], s[58:59]
	s_load_dwordx2 s[0:1], s[0:1], 0x18
	s_mov_b64 s[8:9], s[58:59]
	s_load_dwordx2 s[4:5], s[4:5], 0x150
	s_lshl_b32 s3, s2, 1
	s_load_dwordx2 s[10:11], s[8:9], 0x90
	s_mov_b64 s[8:9], s[58:59]
	s_and_b32 s3, s3, -8
	s_load_dwordx2 s[14:15], s[8:9], 0x158
	v_mbcnt_lo_u32_b32 v102, -1, 0
	v_mbcnt_hi_u32_b32 v102, -1, v102
	s_add_i32 s16, s3, 0x4000
	v_add_u32_e32 v1, s61, v102
	s_ashr_i32 s3, s2, 31
	s_lshl_b64 s[12:13], s[2:3], 14
	s_lshl_b64 s[8:9], s[2:3], 16
	v_ashrrev_i32_e32 v94, 2, v1
	s_waitcnt lgkmcnt(0)
	s_add_u32 s0, s0, s8
	v_and_b32_e32 v0, 0x7f, v1
	v_and_b32_e32 v98, 0xffffffe0, v94
	s_addc_u32 s1, s1, s9
	v_lshlrev_b32_e32 v156, 2, v0
	v_or_b32_e32 v4, 1, v98
	v_or_b32_e32 v6, 2, v98
	v_or_b32_e32 v8, 3, v98
	v_or_b32_e32 v10, 4, v98
	v_or_b32_e32 v12, 5, v98
	v_or_b32_e32 v14, 6, v98
	v_or_b32_e32 v16, 7, v98
	v_lshl_add_u64 v[90:91], s[0:1], 0, v[156:157]
	s_cmpk_lt_i32 s2, 0x100
	s_cbranch_scc0 .Lhsmp_skip
	v_lshlrev_b32_e32 v140, 7, v1
	v_add_u32_e32 v140, 0x1000000, v140
	v_mov_b32_e32 v141, 0
	v_lshl_add_u64 v[140:141], s[0:1], 0, v[140:141]
	global_load_dword v142, v[140:141], off
.Lhsmp_skip:
	v_ashrrev_i32_e32 v99, 31, v98
	v_ashrrev_i32_e32 v5, 31, v4
	v_ashrrev_i32_e32 v7, 31, v6
	v_ashrrev_i32_e32 v9, 31, v8
	v_ashrrev_i32_e32 v11, 31, v10
	v_ashrrev_i32_e32 v13, 31, v12
	v_ashrrev_i32_e32 v15, 31, v14
	v_ashrrev_i32_e32 v17, 31, v16
	s_lshl_b32 s0, s2, 7
	v_lshlrev_b64 v[2:3], 9, v[98:99]
	v_lshlrev_b64 v[4:5], 9, v[4:5]
	v_lshlrev_b64 v[6:7], 9, v[6:7]
	v_lshlrev_b64 v[8:9], 9, v[8:9]
	v_lshlrev_b64 v[10:11], 9, v[10:11]
	v_lshlrev_b64 v[12:13], 9, v[12:13]
	v_lshlrev_b64 v[14:15], 9, v[14:15]
	v_lshlrev_b64 v[16:17], 9, v[16:17]
	s_and_b32 s0, s0, 0x180
	v_lshl_add_u64 v[18:19], v[90:91], 0, v[2:3]
	v_lshl_add_u64 v[20:21], v[90:91], 0, v[4:5]
	v_lshl_add_u64 v[22:23], v[90:91], 0, v[6:7]
	v_lshl_add_u64 v[24:25], v[90:91], 0, v[8:9]
	v_lshl_add_u64 v[28:29], v[90:91], 0, v[10:11]
	v_lshl_add_u64 v[30:31], v[90:91], 0, v[12:13]
	v_lshl_add_u64 v[32:33], v[90:91], 0, v[14:15]
	v_lshl_add_u64 v[34:35], v[90:91], 0, v[16:17]
	s_lshl_b32 s1, s0, 1
	global_load_dword v26, v[18:19], off nt
	global_load_dword v27, v[20:21], off nt
	s_nop 0
	global_load_dword v22, v[22:23], off nt
	s_nop 0
	global_load_dword v23, v[24:25], off nt
	global_load_dword v20, v[28:29], off nt
	global_load_dword v21, v[30:31], off nt
	global_load_dword v18, v[32:33], off nt
	global_load_dword v19, v[34:35], off nt
	v_or_b32_e32 v24, 8, v98
	v_or_b32_e32 v28, 9, v98
	v_or_b32_e32 v30, 10, v98
	v_or_b32_e32 v32, 11, v98
	v_or_b32_e32 v34, 12, v98
	s_add_u32 s8, s18, s1
	v_ashrrev_i32_e32 v25, 31, v24
	v_ashrrev_i32_e32 v29, 31, v28
	v_ashrrev_i32_e32 v31, 31, v30
	v_ashrrev_i32_e32 v33, 31, v32
	v_ashrrev_i32_e32 v35, 31, v34
	v_or_b32_e32 v36, 13, v98
	v_or_b32_e32 v38, 14, v98
	v_or_b32_e32 v40, 15, v98
	s_addc_u32 s9, s19, 0
	v_lshlrev_b32_e32 v72, 1, v0
	v_mov_b32_e32 v73, v157
	v_lshlrev_b64 v[24:25], 9, v[24:25]
	v_lshlrev_b64 v[28:29], 9, v[28:29]
	v_lshlrev_b64 v[30:31], 9, v[30:31]
	v_lshlrev_b64 v[32:33], 9, v[32:33]
	v_lshlrev_b64 v[34:35], 9, v[34:35]
	v_ashrrev_i32_e32 v37, 31, v36
	v_ashrrev_i32_e32 v39, 31, v38
	v_ashrrev_i32_e32 v41, 31, v40
	v_lshl_add_u64 v[72:73], s[8:9], 0, v[72:73]
	v_ashrrev_i32_e32 v76, 7, v1
	v_lshl_add_u64 v[42:43], v[90:91], 0, v[24:25]
	v_lshl_add_u64 v[44:45], v[90:91], 0, v[28:29]
	v_lshl_add_u64 v[46:47], v[90:91], 0, v[30:31]
	v_lshl_add_u64 v[48:49], v[90:91], 0, v[32:33]
	v_lshl_add_u64 v[52:53], v[90:91], 0, v[34:35]
	v_lshlrev_b64 v[36:37], 9, v[36:37]
	v_lshlrev_b64 v[38:39], 9, v[38:39]
	v_lshlrev_b64 v[40:41], 9, v[40:41]
	v_lshl_add_u64 v[72:73], v[72:73], 0, s[46:47]
	v_add_u32_e32 v76, s16, v76
	v_add_u32_e32 v88, 0x200, v1
	v_lshl_add_u64 v[54:55], v[90:91], 0, v[36:37]
	v_lshl_add_u64 v[56:57], v[90:91], 0, v[38:39]
	v_lshl_add_u64 v[58:59], v[90:91], 0, v[40:41]
	global_load_dword v50, v[42:43], off nt
	global_load_dword v51, v[44:45], off nt
	s_nop 0
	global_load_dword v46, v[46:47], off nt
	s_nop 0
	global_load_dword v47, v[48:49], off nt
	global_load_dword v44, v[52:53], off nt
	global_load_dword v45, v[54:55], off nt
	global_load_dword v42, v[56:57], off nt
	global_load_dword v43, v[58:59], off nt
	v_or_b32_e32 v48, 16, v98
	v_or_b32_e32 v52, 17, v98
	v_mad_i64_i32 v[76:77], s[8:9], v76, s83, v[72:73]
	v_ashrrev_i32_e32 v88, 7, v88
	v_ashrrev_i32_e32 v49, 31, v48
	v_ashrrev_i32_e32 v53, 31, v52
	v_or_b32_e32 v54, 18, v98
	v_or_b32_e32 v56, 19, v98
	v_or_b32_e32 v58, 20, v98
	v_or_b32_e32 v60, 21, v98
	v_or_b32_e32 v62, 22, v98
	v_or_b32_e32 v64, 23, v98
	v_add_co_u32_e32 v86, vcc, s72, v76
	v_add_u32_e32 v88, s16, v88
	v_lshlrev_b64 v[48:49], 9, v[48:49]
	v_lshlrev_b64 v[52:53], 9, v[52:53]
	v_ashrrev_i32_e32 v55, 31, v54
	v_ashrrev_i32_e32 v57, 31, v56
	v_ashrrev_i32_e32 v59, 31, v58
	v_ashrrev_i32_e32 v61, 31, v60
	v_ashrrev_i32_e32 v63, 31, v62
	v_ashrrev_i32_e32 v65, 31, v64
	v_addc_co_u32_e32 v87, vcc, 0, v77, vcc
	v_mad_i64_i32 v[72:73], s[8:9], v88, s83, v[72:73]
	v_lshl_add_u64 v[66:67], v[90:91], 0, v[48:49]
	v_lshl_add_u64 v[68:69], v[90:91], 0, v[52:53]
	v_lshlrev_b64 v[54:55], 9, v[54:55]
	v_lshlrev_b64 v[56:57], 9, v[56:57]
	v_lshlrev_b64 v[58:59], 9, v[58:59]
	v_lshlrev_b64 v[60:61], 9, v[60:61]
	v_lshlrev_b64 v[62:63], 9, v[62:63]
	v_lshlrev_b64 v[64:65], 9, v[64:65]
	v_add_co_u32_e32 v88, vcc, s72, v72
	v_lshl_add_u64 v[70:71], v[90:91], 0, v[54:55]
	v_lshl_add_u64 v[74:75], v[90:91], 0, v[56:57]
	v_lshl_add_u64 v[78:79], v[90:91], 0, v[58:59]
	v_lshl_add_u64 v[80:81], v[90:91], 0, v[60:61]
	v_lshl_add_u64 v[82:83], v[90:91], 0, v[62:63]
	v_lshl_add_u64 v[84:85], v[90:91], 0, v[64:65]
	v_addc_co_u32_e32 v89, vcc, 0, v73, vcc
	global_load_ushort v99, v[86:87], off
	global_load_ushort v103, v[86:87], off offset:1024
	global_load_ushort v114, v[86:87], off offset:2048
	global_load_ushort v115, v[88:89], off
	global_load_ushort v116, v[88:89], off offset:1024
	global_load_ushort v117, v[88:89], off offset:2048
	global_load_ushort v118, v[72:73], off offset:3072
	global_load_ushort v119, v[76:77], off offset:3072
	s_nop 0
	global_load_dword v76, v[66:67], off nt
	global_load_dword v77, v[68:69], off nt
	global_load_dword v72, v[70:71], off nt
	global_load_dword v73, v[74:75], off nt
	s_nop 0
	global_load_dword v68, v[78:79], off nt
	global_load_dword v69, v[80:81], off nt
	global_load_dword v66, v[82:83], off nt
	global_load_dword v67, v[84:85], off nt
	v_or_b32_e32 v70, 24, v98
	v_or_b32_e32 v74, 25, v98
	v_or_b32_e32 v78, 26, v98
	v_ashrrev_i32_e32 v71, 31, v70
	v_ashrrev_i32_e32 v75, 31, v74
	v_ashrrev_i32_e32 v79, 31, v78
	v_or_b32_e32 v80, 27, v98
	v_or_b32_e32 v82, 28, v98
	v_or_b32_e32 v84, 29, v98
	v_or_b32_e32 v86, 30, v98
	v_or_b32_e32 v88, 31, v94
	v_lshlrev_b64 v[70:71], 9, v[70:71]
	v_lshlrev_b64 v[74:75], 9, v[74:75]
	v_lshlrev_b64 v[78:79], 9, v[78:79]
	v_ashrrev_i32_e32 v81, 31, v80
	v_ashrrev_i32_e32 v83, 31, v82
	v_ashrrev_i32_e32 v85, 31, v84
	v_ashrrev_i32_e32 v87, 31, v86
	v_ashrrev_i32_e32 v89, 31, v88
	v_lshl_add_u64 v[92:93], v[90:91], 0, v[70:71]
	v_lshl_add_u64 v[96:97], v[90:91], 0, v[74:75]
	v_lshl_add_u64 v[100:101], v[90:91], 0, v[78:79]
	v_lshlrev_b64 v[80:81], 9, v[80:81]
	v_lshlrev_b64 v[82:83], 9, v[82:83]
	v_lshlrev_b64 v[84:85], 9, v[84:85]
	v_lshlrev_b64 v[86:87], 9, v[86:87]
	v_lshlrev_b64 v[88:89], 9, v[88:89]
	v_lshl_add_u64 v[104:105], v[90:91], 0, v[80:81]
	v_lshl_add_u64 v[106:107], v[90:91], 0, v[82:83]
	v_lshl_add_u64 v[108:109], v[90:91], 0, v[84:85]
	v_lshl_add_u64 v[110:111], v[90:91], 0, v[86:87]
	v_lshl_add_u64 v[112:113], v[90:91], 0, v[88:89]
	global_load_dword v94, v[92:93], off nt
	global_load_dword v95, v[96:97], off nt
	s_nop 0
	global_load_dword v92, v[100:101], off nt
	global_load_dword v93, v[104:105], off nt
	global_load_dword v90, v[106:107], off nt
	global_load_dword v91, v[108:109], off nt
	global_load_dword v96, v[110:111], off nt
	s_nop 0
	global_load_dword v100, v[112:113], off nt
	s_lshl_b32 s1, s0, 2
	s_add_i32 s1, s1, 0
	v_add_u32_e32 v97, s1, v156
	v_add_u32_e32 v97, 0x22400, v97
	s_mov_b32 s1, 0
	v_lshl_add_u32 v98, v98, 2, 0
	s_waitcnt vmcnt(0)
	v_lshlrev_b32_e32 v99, 16, v99
	v_mul_f32_e32 v99, 0xbfb8aa3b, v99
	v_exp_f32_e32 v99, v99
	v_lshlrev_b32_e32 v101, 16, v103
	ds_read_b32 v103, v97
	v_lshlrev_b32_e32 v105, 16, v114
	v_add_f32_e32 v99, 1.0, v99
	v_lshlrev_b32_e32 v104, 16, v119
	v_mul_f32_e32 v107, 0xbfb8aa3b, v104
	v_exp_f32_e32 v107, v107
	v_rcp_f32_e32 v99, v99
	s_waitcnt lgkmcnt(0)
	v_sub_f32_e32 v106, 1.0, v103
	v_add_f32_e32 v107, 1.0, v107
	v_rcp_f32_e32 v107, v107
	v_fmac_f32_e32 v103, v106, v99
	v_lshlrev_b32_e32 v106, 2, v1
	v_add_u32_e32 v99, 0, v106
	ds_write_b32 v99, v103
	v_sub_f32_e32 v103, 1.0, v103
	ds_write_b32 v99, v103 offset:4096
	v_mul_f32_e32 v103, v107, v104
	ds_write_b32 v99, v103 offset:8192
	ds_write_b32 v99, v101 offset:12288
	ds_write_b32 v99, v105 offset:16384
	v_lshlrev_b32_e32 v101, 16, v115
	v_mul_f32_e32 v101, 0xbfb8aa3b, v101
	v_exp_f32_e32 v101, v101
	v_lshlrev_b32_e32 v104, 16, v118
	ds_read_b32 v97, v97
	v_mul_f32_e32 v105, 0xbfb8aa3b, v104
	v_add_f32_e32 v101, 1.0, v101
	v_rcp_f32_e32 v101, v101
	v_exp_f32_e32 v105, v105
	s_waitcnt lgkmcnt(0)
	v_sub_f32_e32 v108, 1.0, v97
	v_lshlrev_b32_e32 v103, 16, v116
	v_fmac_f32_e32 v97, v108, v101
	v_add_f32_e32 v101, 1.0, v105
	v_rcp_f32_e32 v101, v101
	ds_write_b32 v99, v97 offset:2048
	v_sub_f32_e32 v97, 1.0, v97
	ds_write_b32 v99, v97 offset:6144
	v_mul_f32_e32 v97, v101, v104
	v_lshlrev_b32_e32 v107, 16, v117
	ds_write_b32 v99, v97 offset:10240
	ds_write_b32 v99, v103 offset:14336
	ds_write_b32 v99, v107 offset:18432
	v_and_b32_e32 v97, 0xfffffe00, v106
	v_add_u32_e32 v99, 0, v156
	v_add_u32_e32 v103, 0x5000, v97
	s_waitcnt lgkmcnt(0)
	s_barrier
